# grid barrier: four polls in flight, re-issued as each returns
# speedup vs baseline: 1.0010x; 1.0010x over previous
; __device__ __forceinline__ unsigned xb_ld(unsigned* p)              { return __hip_atomic_load(p, __ATOMIC_RELAXED, __HIP_MEMORY_SCOPE_AGENT); }
; __device__ __forceinline__ unsigned xb_add(unsigned* p, unsigned v) { return __hip_atomic_fetch_add(p, v, __ATOMIC_RELAXED, __HIP_MEMORY_SCOPE_AGENT); }
; #define XB_SPIN(cond, bar) do { unsigned _sp = 0; while (cond) { __builtin_amdgcn_s_sleep(1); \
;     if ((++_sp & 255u) == 0u) { if (xb_ld(&(bar)[XB_TMO])) break; if (_sp > XB_SPIN_CAP) { atomicAdd(&(bar)[XB_TMO], 1u); break; } } } } while (0)
; __device__ __forceinline__ void xcd_barrier(const XcdBarrier& b) {
;     ...
;             else XB_SPIN(xb_ld(&bar[XB_TOPGEN]) == tg, bar);
;             __builtin_amdgcn_fence(__ATOMIC_ACQUIRE, "agent");
;             xb_add(&bar[XB_XGEN(b.x)], 1u);
;             asm volatile("s_waitcnt vmcnt(0)" ::: "memory");
;         } else {
;             XB_SPIN(xb_ld(&bar[XB_XGEN(b.x)]) == gen, bar);
.Lxb_poll_0:
	s_mov_b32 s18, 0
	global_load_dword v0, v3, s[16:17] sc1
	s_sleep 4
	global_load_dword v1, v3, s[16:17] sc1
	s_sleep 4
	global_load_dword v2, v3, s[16:17] sc1
	s_sleep 4
	global_load_dword v5, v3, s[16:17] sc1
.Lxb_spin_0:
	s_waitcnt vmcnt(3)
	v_readfirstlane_b32 s19, v0
	s_cmp_ge_u32 s19, s15
	s_cbranch_scc1 .Lxb_done_0
	global_load_dword v0, v3, s[16:17] sc1
	s_waitcnt vmcnt(3)
	v_readfirstlane_b32 s19, v1
	s_cmp_ge_u32 s19, s15
	s_cbranch_scc1 .Lxb_done_0
	global_load_dword v1, v3, s[16:17] sc1
	s_waitcnt vmcnt(3)
	v_readfirstlane_b32 s19, v2
	s_cmp_ge_u32 s19, s15
	s_cbranch_scc1 .Lxb_done_0
	global_load_dword v2, v3, s[16:17] sc1
	s_waitcnt vmcnt(3)
	v_readfirstlane_b32 s19, v5
	s_cmp_ge_u32 s19, s15
	s_cbranch_scc1 .Lxb_done_0
	global_load_dword v5, v3, s[16:17] sc1
	s_add_i32 s18, s18, 4
	s_cmp_lt_u32 s18, 0x100000
	s_cbranch_scc1 .Lxb_spin_0
